# plus layer-0 x to bf16 conversion loop with the four row loads in flight together
# baseline (speedup 1.0000x reference)
; __device__ __forceinline__ unsigned pk2(float lo, float hi) { f32x2 v = {lo, hi}; bf16x2_t b = __builtin_convertvector(v, bf16x2_t); return __builtin_bit_cast(unsigned, b); }
; __device__ __forceinline__ void prep_phase(const Params& p, int l, LAS unsigned char* lds) {
;     ...
;         for (int m = gw; m < S; m += NGW) {
;             const f32x4* xr = (const f32x4*)(p.x + (size_t)m * D) + lane; u32x2* o8 = (u32x2*)(xb + (size_t)m * D) + lane; float s = 0.f;
; #pragma unroll
;             for (int j = 0; j < 4; ++j) { const f32x4 v = xr[64 * j]; s += (v[0] * v[0] + v[1] * v[1]) + (v[2] * v[2] + v[3] * v[3]); u32x2 w; w.x = pk2(v[0], v[1]); w.y = pk2(v[2], v[3]); o8[64 * j] = w; }
;             s = wave_sum(s);
;             if (lane < 16) ssq[(size_t)m * 16 + lane] = lane == 0 ? s : 0.f;
;         }
.LBB0_52:
	s_waitcnt lgkmcnt(0)
	global_load_dwordx4 v[12:15], v[4:5], off offset:-3072
	global_load_dwordx4 v[24:27], v[4:5], off offset:-2048
	global_load_dwordx4 v[28:31], v[4:5], off offset:-1024
	global_load_dwordx4 v[32:35], v[4:5], off
	v_lshl_add_u64 v[16:17], s[30:31], 0, v[2:3]
	s_brev_b32 s0, 64
	v_add_co_u32_e32 v16, vcc, s0, v16
	s_nop 1
	v_addc_co_u32_e32 v17, vcc, 0, v17, vcc
	s_waitcnt vmcnt(3)
	v_mul_f32_e32 v18, v13, v13
	v_fmac_f32_e32 v18, v12, v12
	v_mul_f32_e32 v19, v15, v15
	v_fmac_f32_e32 v19, v14, v14
	v_add_f32_e32 v18, v18, v19
	v_cvt_pk_bf16_f32 v12, v12, v13
	v_cvt_pk_bf16_f32 v13, v14, v15
	global_store_dwordx2 v[16:17], v[12:13], off
	s_waitcnt vmcnt(3)
	v_mul_f32_e32 v19, v25, v25
	v_fmac_f32_e32 v19, v24, v24
	v_mul_f32_e32 v20, v27, v27
	v_fmac_f32_e32 v20, v26, v26
	v_add_f32_e32 v19, v19, v20
	v_add_f32_e32 v18, v18, v19
	v_cvt_pk_bf16_f32 v24, v24, v25
	v_cvt_pk_bf16_f32 v25, v26, v27
	global_store_dwordx2 v[16:17], v[24:25], off offset:512
	s_waitcnt vmcnt(3)
	v_mul_f32_e32 v19, v29, v29
	v_fmac_f32_e32 v19, v28, v28
	v_mul_f32_e32 v20, v31, v31
	v_fmac_f32_e32 v20, v30, v30
	v_add_f32_e32 v19, v19, v20
	v_add_f32_e32 v18, v18, v19
	v_cvt_pk_bf16_f32 v28, v28, v29
	v_cvt_pk_bf16_f32 v29, v30, v31
	global_store_dwordx2 v[16:17], v[28:29], off offset:1024
	s_waitcnt vmcnt(3)
	v_mul_f32_e32 v19, v33, v33
	v_fmac_f32_e32 v19, v32, v32
	v_mul_f32_e32 v20, v35, v35
	v_fmac_f32_e32 v20, v34, v34
	v_add_f32_e32 v19, v19, v20
	v_add_f32_e32 v18, v18, v19
	v_cvt_pk_bf16_f32 v32, v32, v33
	v_cvt_pk_bf16_f32 v33, v34, v35
	global_store_dwordx2 v[16:17], v[32:33], off offset:1536
	ds_bpermute_b32 v12, v6, v18
	s_waitcnt lgkmcnt(0)
	v_add_f32_e32 v12, v18, v12
	ds_bpermute_b32 v13, v7, v12
	s_waitcnt lgkmcnt(0)
	v_add_f32_e32 v12, v12, v13
	ds_bpermute_b32 v13, v8, v12
	s_waitcnt lgkmcnt(0)
	v_add_f32_e32 v12, v12, v13
	ds_bpermute_b32 v13, v9, v12
	s_waitcnt lgkmcnt(0)
	v_add_f32_e32 v12, v12, v13
	ds_bpermute_b32 v13, v10, v12
	s_waitcnt lgkmcnt(0)
	v_add_f32_e32 v12, v12, v13
	ds_bpermute_b32 v13, v11, v12
	s_and_saveexec_b64 s[0:1], s[4:5]
	s_cbranch_execz .LBB0_51
	s_waitcnt lgkmcnt(0)
	v_add_f32_e32 v12, v12, v13
	v_cndmask_b32_e64 v14, 0, v12, s[6:7]
	v_lshl_add_u64 v[12:13], s[30:31], 0, v[0:1]
	global_store_dword v[12:13], v14, off
	s_branch .LBB0_51
